# A loop odd tile: removed hipcc 52-move register rotation (temporaries now in dead staging set B)
# speedup vs baseline: 1.0195x; 1.0051x over previous
; template <int NC, bool DIAG>
; __device__ __forceinline__ void attn_tile(f32x16 (&O)[4], float& l, const bf16x8* Q, const LAS char* Kb, const LAS char* Vb, int r32, int hi, int lane, float qd, int k0, int qw, float nslope, float negM0) {
;     constexpr int NQ = (NC == 2) ? 4 : 8;
;     f32x16 S0, S1; bf16x8 P0[2], P1[2];
;     const int k1 = k0 + 32;
;     if (NC == 2) {
;         const float ns0 = (k0 < qw) ? nslope : ((k0 > qw) ? -nslope : 0.f), ns1 = (k1 < qw) ? nslope : ((k1 > qw) ? -nslope : 0.f);
;         const float b0 = fmaf(ns0, qd - (float)k0, negM0), b1 = fmaf(ns1, qd - (float)k1, negM0);
; #pragma unroll
;         for (int r = 0; r < 16; ++r) { S0[r] = fmaf(-ns0, (float)((r & 3) + 8 * (r >> 2)), b0); S1[r] = fmaf(-ns1, (float)((r & 3) + 8 * (r >> 2)), b1); }
.LBB0_281:
	ds_read_b128 v[16:19], v227 offset:37888
	ds_read_b128 v[20:23], v227 offset:37920
	ds_read_b128 v[24:27], v227 offset:37952
	ds_read_b128 v[28:31], v227 offset:37984
	s_mov_b32 s26, s89
	s_add_i32 s78, s26, 32
	s_cmp_lt_i32 s26, s87
	s_cselect_b64 vcc, -1, 0
	s_cmp_gt_i32 s26, s87
	s_cselect_b64 s[4:5], -1, 0
	v_cndmask_b32_e64 v0, 0, -v225, s[4:5]
	s_cmp_lt_i32 s78, s87
	v_cndmask_b32_e32 v218, v0, v225, vcc
	v_cvt_f32_i32_e32 v0, s26
	v_cvt_f32_i32_e32 v2, s78
	s_cselect_b64 s[4:5], -1, 0
	s_cmp_gt_i32 s78, s87
	s_cselect_b64 s[92:93], -1, 0
	v_cndmask_b32_e64 v1, 0, -v225, s[92:93]
	v_cndmask_b32_e64 v220, v1, v225, s[4:5]
	v_sub_f32_e32 v234, v219, v0
	v_sub_f32_e32 v233, v219, v2
	v_fma_f32 v142, v218, v234, v254
	v_fma_f32 v224, v220, v233, v254
	s_cmp_lg_u32 s91, 2
	v_fmamk_f32 v144, v218, 0x80000000, v142
	v_fmamk_f32 v128, v220, 0x80000000, v224
	s_mov_b64 s[4:5], -1
	v_sub_f32_e32 v145, v142, v218
	v_sub_f32_e32 v129, v224, v220
	s_cbranch_scc0 .LBB0_284
; #define SCHED_FENCE() __builtin_amdgcn_sched_barrier(0)
; #define LOADB(tt) do { const char* kp_ = kgp + (size_t)(tt) * tstep; const char* vp_ = vgp + (size_t)(tt) * tstep; kb0 = *(const u32x4*)kp_; kb1 = *(const u32x4*)(kp_ + 16); vb0 = *(const u32x4*)vp_; vb1 = *(const u32x4*)(vp_ + 16); } while (0)
; template <int NC, bool DIAG>
; __device__ __forceinline__ void attn_tile(f32x16 (&O)[4], float& l, const bf16x8* Q, const LAS char* Kb, const LAS char* Vb, int r32, int hi, int lane, float qd, int k0, int qw, float nslope, float negM0) {
;     ...
;     if (NC == 2) {
;         bf16x8 kf0[NQ], kf1[NQ];
;         kload32<NQ>(kf0, Kb, r32, hi);
;         SCHED_FENCE();
;         qkmm32<NQ>(S0, kf0, Q);
;         kload32<NQ>(kf1, Kb + 32 * KP, r32, hi);
;         vload16<0>(vf0, Vb, lane);
;         SCHED_FENCE();
;         qkmm32<NQ>(S1, kf1, Q);
;         if (DIAG) { const float nd = (k0 == qw) ? nslope : 0.f;
; #pragma unroll
;             for (int r = 0; r < 16; ++r) S0[r] = fmaf(nd, fabsf(qd - (float)k0 - (float)((r & 3) + 8 * (r >> 2))), S0[r]); }
;         soft32<0>(S0, P0, l, 0.f, 0.f);
;         vload16<1>(vf0, Vb, lane);
;         SCHED_FENCE();
;     } else {
;         bf16x8 kf[NQ];
;         kload32<NQ>(kf, Kb, r32, hi);
;         SCHED_FENCE();
;         qkmm32<NQ>(S0, kf, Q);
;         kload32<NQ>(kf, Kb + 32 * KP, r32, hi);
;         vload32(vf0, Vb, lane);
;         SCHED_FENCE();
;         qkmm32<NQ>(S1, kf, Q);
;         soft32<0>(S0, P0, l, 0.f, 0.f);
;         SCHED_FENCE();
;     }
;     pvmm32(O, P0, vf0);
;     if (NC == 2 && DIAG) { const float nd = (k1 == qw) ? nslope : 0.f;
; #pragma unroll
;         for (int r = 0; r < 16; ++r) S1[r] = fmaf(nd, fabsf(qd - (float)k1 - (float)((r & 3) + 8 * (r >> 2))), S1[r]); }
;     soft32<0>(S1, P1, l, 0.f, 0.f);
;     if (NC == 2) {
;     vload16<0>(vf1, Vb + 32 * VP, lane);
;     SCHED_FENCE();
;     vload16<1>(vf1, Vb + 32 * VP, lane);
;     } else {
;     vload32(vf1, Vb + 32 * VP, lane);
;     SCHED_FENCE();
;     }
;     pvmm32(O, P1, vf1);
; template <int NC>
; __device__ __forceinline__ void attn_shared_unit(LAS char* lds, bf16* qbase, const bf16* Kg, const bf16* Vg, int kvp, int nt, int qpos, int qw, float nslope, float negM0, float lam, const float* subln, int wave_id) {
;     ...
;             if (t + 3 < t_hi) LOADB(t + 3);
	v_pk_fma_f32 v[146:147], v[218:219], s[22:23], v[142:143] op_sel_hi:[0,1,0] neg_lo:[1,0,0] neg_hi:[1,0,0]
	v_pk_fma_f32 v[148:149], v[218:219], s[44:45], v[142:143] op_sel_hi:[0,1,0] neg_lo:[1,0,0] neg_hi:[1,0,0]
	v_pk_fma_f32 v[150:151], v[218:219], s[46:47], v[142:143] op_sel_hi:[0,1,0] neg_lo:[1,0,0] neg_hi:[1,0,0]
	v_pk_fma_f32 v[152:153], v[218:219], s[48:49], v[142:143] op_sel_hi:[0,1,0] neg_lo:[1,0,0] neg_hi:[1,0,0]
	v_pk_fma_f32 v[154:155], v[218:219], s[50:51], v[142:143] op_sel_hi:[0,1,0] neg_lo:[1,0,0] neg_hi:[1,0,0]
	v_pk_fma_f32 v[156:157], v[218:219], s[52:53], v[142:143] op_sel_hi:[0,1,0] neg_lo:[1,0,0] neg_hi:[1,0,0]
	v_pk_fma_f32 v[158:159], v[218:219], s[54:55], v[142:143] op_sel_hi:[0,1,0] neg_lo:[1,0,0] neg_hi:[1,0,0]
	v_pk_fma_f32 v[142:143], v[220:221], s[54:55], v[224:225] op_sel_hi:[0,1,0] neg_lo:[1,0,0] neg_hi:[1,0,0]
	v_pk_fma_f32 v[130:131], v[220:221], s[22:23], v[224:225] op_sel_hi:[0,1,0] neg_lo:[1,0,0] neg_hi:[1,0,0]
	v_pk_fma_f32 v[132:133], v[220:221], s[44:45], v[224:225] op_sel_hi:[0,1,0] neg_lo:[1,0,0] neg_hi:[1,0,0]
	v_pk_fma_f32 v[134:135], v[220:221], s[46:47], v[224:225] op_sel_hi:[0,1,0] neg_lo:[1,0,0] neg_hi:[1,0,0]
	v_pk_fma_f32 v[136:137], v[220:221], s[48:49], v[224:225] op_sel_hi:[0,1,0] neg_lo:[1,0,0] neg_hi:[1,0,0]
	v_pk_fma_f32 v[138:139], v[220:221], s[50:51], v[224:225] op_sel_hi:[0,1,0] neg_lo:[1,0,0] neg_hi:[1,0,0]
	v_pk_fma_f32 v[140:141], v[220:221], s[52:53], v[224:225] op_sel_hi:[0,1,0] neg_lo:[1,0,0] neg_hi:[1,0,0]
	s_waitcnt lgkmcnt(3)
	s_nop 0
	v_mfma_f32_32x32x16_bf16 v[0:15], v[16:19], v[162:165], v[144:159]
	s_waitcnt lgkmcnt(2)
	v_mfma_f32_32x32x16_bf16 v[0:15], v[20:23], v[166:169], v[0:15]
	ds_read_b128 v[16:19], v227 offset:46592
	ds_read_b128 v[20:23], v227 offset:46624
	ds_read_b128 v[32:35], v227 offset:46656
	ds_read_b128 v[36:39], v227 offset:46688
	s_waitcnt lgkmcnt(5)
	v_mfma_f32_32x32x16_bf16 v[0:15], v[24:27], v[170:173], v[0:15]
	ds_read_b64_tr_b16 v[24:25], v226 offset:55296
	ds_read_b64_tr_b16 v[236:237], v226 offset:55360
	ds_read_b64_tr_b16 v[240:241], v226 offset:55424
	ds_read_b64_tr_b16 v[244:245], v226 offset:55488
	ds_read_b64_tr_b16 v[26:27], v226 offset:57856
	ds_read_b64_tr_b16 v[238:239], v226 offset:57920
	ds_read_b64_tr_b16 v[242:243], v226 offset:57984
	ds_read_b64_tr_b16 v[246:247], v226 offset:58048
	s_waitcnt lgkmcnt(12)
	v_mfma_f32_32x32x16_bf16 v[0:15], v[28:31], v[174:177], v[0:15]
	s_nop 11
	v_exp_f32_e32 v0, v0
	v_exp_f32_e32 v1, v1
	s_waitcnt lgkmcnt(11)
	v_mfma_f32_32x32x16_bf16 v[146:161], v[16:19], v[162:165], v[128:143]
	v_exp_f32_e32 v2, v2
	v_exp_f32_e32 v3, v3
	v_add_f32_e32 v28, v232, v0
	v_exp_f32_e32 v4, v4
	v_add_f32_e32 v16, v1, v28
	v_exp_f32_e32 v5, v5
	v_add_f32_e32 v16, v2, v16
	s_waitcnt lgkmcnt(10)
	v_mfma_f32_32x32x16_bf16 v[146:161], v[20:23], v[166:169], v[146:161]
	v_exp_f32_e32 v6, v6
	v_add_f32_e32 v16, v3, v16
	v_exp_f32_e32 v7, v7
	v_add_f32_e32 v16, v4, v16
	v_exp_f32_e32 v8, v8
	s_waitcnt lgkmcnt(9)
	v_mfma_f32_32x32x16_bf16 v[146:161], v[32:35], v[170:173], v[146:161]
	v_add_f32_e32 v16, v5, v16
	v_exp_f32_e32 v9, v9
	v_add_f32_e32 v16, v6, v16
	v_exp_f32_e32 v10, v10
	v_add_f32_e32 v16, v7, v16
	v_exp_f32_e32 v11, v11
	v_add_f32_e32 v16, v8, v16
	v_exp_f32_e32 v12, v12
	ds_read_b64_tr_b16 v[134:135], v226 offset:60416
	ds_read_b64_tr_b16 v[138:139], v226 offset:60480
	ds_read_b64_tr_b16 v[248:249], v226 offset:60544
	ds_read_b64_tr_b16 v[182:183], v226 offset:60608
	ds_read_b64_tr_b16 v[136:137], v226 offset:62976
	ds_read_b64_tr_b16 v[140:141], v226 offset:63040
	ds_read_b64_tr_b16 v[250:251], v226 offset:63104
	ds_read_b64_tr_b16 v[184:185], v226 offset:63168
	v_add_f32_e32 v16, v9, v16
	v_exp_f32_e32 v13, v13
	s_waitcnt lgkmcnt(14)
	v_mfma_f32_32x32x16_bf16 v[146:161], v[36:39], v[174:177], v[146:161]
	v_add_f32_e32 v16, v10, v16
	v_exp_f32_e32 v14, v14
	v_add_f32_e32 v16, v11, v16
	v_exp_f32_e32 v15, v15
	v_add_f32_e32 v16, v12, v16
	v_add_f32_e32 v16, v13, v16
	v_add_f32_e32 v16, v14, v16
	v_add_f32_e32 v16, v15, v16
	v_cvt_pk_bf16_f32 v186, v8, v9
	v_cvt_pk_bf16_f32 v187, v10, v11
	v_cvt_pk_bf16_f32 v188, v12, v13
	v_cvt_pk_bf16_f32 v189, v14, v15
	v_cvt_pk_bf16_f32 v130, v0, v1
	v_cvt_pk_bf16_f32 v131, v2, v3
	v_cvt_pk_bf16_f32 v132, v4, v5
	v_cvt_pk_bf16_f32 v133, v6, v7
	v_exp_f32_e32 v142, v146
	v_exp_f32_e32 v143, v147
	v_exp_f32_e32 v146, v148
	v_exp_f32_e32 v147, v149
	v_add_f32_e32 v0, v16, v142
	v_exp_f32_e32 v148, v150
	v_add_f32_e32 v0, v143, v0
	v_exp_f32_e32 v149, v151
	v_add_f32_e32 v0, v146, v0
	v_exp_f32_e32 v150, v152
	v_add_f32_e32 v0, v147, v0
	v_exp_f32_e32 v151, v153
	v_add_f32_e32 v0, v148, v0
	v_exp_f32_e32 v153, v154
	s_waitcnt lgkmcnt(11)
	v_mfma_f32_32x32x16_bf16 v[48:63], v[24:27], v[130:133], v[64:79]
	v_add_f32_e32 v0, v149, v0
	v_exp_f32_e32 v154, v155
	v_add_f32_e32 v0, v150, v0
	v_exp_f32_e32 v155, v156
	v_add_f32_e32 v152, v151, v0
	v_exp_f32_e32 v156, v157
	v_exp_f32_e32 v157, v159
	s_waitcnt lgkmcnt(10)
	v_mfma_f32_32x32x16_bf16 v[32:47], v[236:239], v[130:133], v[80:95]
	s_waitcnt lgkmcnt(9)
	v_mfma_f32_32x32x16_bf16 v[16:31], v[240:243], v[130:133], v[96:111]
	s_waitcnt lgkmcnt(8)
	v_mfma_f32_32x32x16_bf16 v[0:15], v[244:247], v[130:133], v[112:127]
	v_add_f32_e32 v130, v153, v152
	v_exp_f32_e32 v152, v158
	v_add_f32_e32 v130, v154, v130
	v_add_f32_e32 v130, v155, v130
	v_add_f32_e32 v130, v156, v130
	v_add_f32_e32 v130, v152, v130
	v_add_f32_e32 v130, v157, v130
	s_waitcnt lgkmcnt(3)
	v_mfma_f32_32x32x16_bf16 v[48:63], v[134:137], v[186:189], v[48:63]
	v_cvt_pk_bf16_f32 v131, v146, v147
	v_cvt_pk_bf16_f32 v132, v148, v149
	v_cvt_pk_bf16_f32 v133, v150, v151
	v_cvt_pk_bf16_f32 v134, v153, v154
	v_cvt_pk_bf16_f32 v135, v155, v156
	v_cvt_pk_bf16_f32 v136, v152, v157
	v_exp_f32_e32 v137, v160
	s_waitcnt lgkmcnt(2)
	v_mfma_f32_32x32x16_bf16 v[32:47], v[138:141], v[186:189], v[32:47]
	ds_read_b64_tr_b16 v[138:139], v221
	ds_read_b64_tr_b16 v[146:147], v221 offset:64
	ds_read_b64_tr_b16 v[150:151], v221 offset:128
	ds_read_b64_tr_b16 v[154:155], v221 offset:192
	ds_read_b64_tr_b16 v[140:141], v221 offset:2560
	ds_read_b64_tr_b16 v[148:149], v221 offset:2624
	ds_read_b64_tr_b16 v[152:153], v221 offset:2688
	ds_read_b64_tr_b16 v[156:157], v221 offset:2752
	v_exp_f32_e32 v158, v161
	v_add_f32_e32 v130, v137, v130
	v_add_f32_e32 v229, v158, v130
	v_cvt_pk_bf16_f32 v130, v142, v143
	s_waitcnt lgkmcnt(9)
	v_mfma_f32_32x32x16_bf16 v[16:31], v[248:251], v[186:189], v[16:31]
	v_fma_f32 v142, v218, v234, v254
	v_cvt_pk_bf16_f32 v137, v137, v158
	s_waitcnt lgkmcnt(8)
	v_mfma_f32_32x32x16_bf16 v[0:15], v[182:185], v[186:189], v[0:15]
	s_waitcnt vmcnt(0)
	s_cmp_ge_i32 s88, s57
	s_cbranch_scc1 .Lmy_a_ldb_skip1
	global_load_dwordx4 v[182:185], v[216:217], off offset:-1024
	global_load_dwordx4 v[186:189], v[216:217], off offset:-1040
	global_load_dwordx4 v[198:201], v[216:217], off
	global_load_dwordx4 v[210:213], v[216:217], off offset:-16
